# last-unit 'next unit' prefetch redirected from the unit's cold K-tiles 0,1 to its most recent K-tiles (L2-hot), on top of v76
# speedup vs baseline: 1.0016x; 1.0016x over previous
.LBB0_123:
	s_lshl_b32 s3, s43, 20
	s_and_b64 s[6:7], s[4:5], exec
	s_cselect_b32 s6, s3, s10
	s_lshl_b32 s88, s46, 20
	s_and_b64 s[12:13], s[4:5], exec
	s_cselect_b32 s7, s88, s11
	s_cselect_b32 s98, 0, 0xf00
	s_add_i32 s6, s6, s98
	s_add_i32 s7, s7, s98
	s_add_i32 s8, s9, -2
	s_lshl_b32 s9, s9, 7
	s_addk_i32 s11, 0x100
	s_movk_i32 s12, 0xf00

.LBB0_522:
	v_mov_b32_e32 v4, v2
	v_mov_b32_e32 v5, v2
	s_mul_i32 s86, s85, 0x180000
	s_and_b64 s[4:5], s[0:1], exec
	s_mul_i32 s87, s84, 0x180000
	v_lshl_or_b32 v162, s62, 8, v170
	v_mov_b32_e32 v3, v2
	s_waitcnt vmcnt(38)
	v_mov_b64_e32 v[8:9], v[4:5]
	s_waitcnt vmcnt(34)
	v_mov_b64_e32 v[12:13], v[4:5]
	s_waitcnt vmcnt(22)
	v_mov_b64_e32 v[24:25], v[4:5]
	s_waitcnt vmcnt(18)
	v_mov_b64_e32 v[28:29], v[4:5]
	v_mov_b64_e32 v[40:41], v[4:5]
	v_mov_b64_e32 v[44:45], v[4:5]
	v_mov_b64_e32 v[56:57], v[4:5]
	v_mov_b64_e32 v[60:61], v[4:5]
	v_mov_b64_e32 v[16:17], v[4:5]
	v_mov_b64_e32 v[20:21], v[4:5]
	s_waitcnt vmcnt(16)
	v_mov_b64_e32 v[32:33], v[4:5]
	v_mov_b64_e32 v[36:37], v[4:5]
	v_mov_b64_e32 v[48:49], v[4:5]
	v_mov_b64_e32 v[52:53], v[4:5]
	v_mov_b64_e32 v[64:65], v[4:5]
	v_mov_b64_e32 v[68:69], v[4:5]
	v_mov_b64_e32 v[72:73], v[4:5]
	v_mov_b64_e32 v[76:77], v[4:5]
	v_mov_b64_e32 v[88:89], v[4:5]
	v_mov_b64_e32 v[92:93], v[4:5]
	v_mov_b64_e32 v[104:105], v[4:5]
	v_mov_b64_e32 v[108:109], v[4:5]
	v_mov_b64_e32 v[120:121], v[4:5]
	v_mov_b64_e32 v[124:125], v[4:5]
	v_mov_b64_e32 v[80:81], v[4:5]
	v_mov_b64_e32 v[84:85], v[4:5]
	v_mov_b64_e32 v[96:97], v[4:5]
	v_mov_b64_e32 v[100:101], v[4:5]
	v_mov_b64_e32 v[112:113], v[4:5]
	v_mov_b64_e32 v[116:117], v[4:5]
	v_mov_b64_e32 v[128:129], v[4:5]
	v_mov_b64_e32 v[132:133], v[4:5]
	s_cselect_b32 s89, s86, s88
	s_cselect_b32 s90, s87, s91
	s_cselect_b32 s94, 0, 0x1600
	s_cmp_eq_u32 s98, 32
	s_cselect_b32 s94, s94, 0
	s_add_i32 s89, s89, s94
	s_add_i32 s90, s90, s94
	s_sub_i32 s92, 32, s98
	s_lshl_b32 s92, s92, 8
	s_sub_i32 s89, s89, s92
	s_sub_i32 s90, s90, s92
	v_lshl_add_u32 v164, s63, 8, v169
	v_ashrrev_i32_e32 v163, 31, v162
	s_addk_i32 s91, 0x100
	s_mov_b32 s92, 0
	s_mov_b64 s[62:63], 0
	v_mov_b64_e32 v[6:7], v[2:3]
	v_mov_b64_e32 v[10:11], v[2:3]
	v_mov_b64_e32 v[22:23], v[2:3]
	v_mov_b64_e32 v[26:27], v[2:3]
	v_mov_b64_e32 v[38:39], v[2:3]
	v_mov_b64_e32 v[42:43], v[2:3]
	v_mov_b64_e32 v[54:55], v[2:3]
	v_mov_b64_e32 v[58:59], v[2:3]
	v_mov_b64_e32 v[14:15], v[2:3]
	v_mov_b64_e32 v[18:19], v[2:3]
	v_mov_b64_e32 v[30:31], v[2:3]
	v_mov_b64_e32 v[34:35], v[2:3]
	v_mov_b64_e32 v[46:47], v[2:3]
	v_mov_b64_e32 v[50:51], v[2:3]
	v_mov_b64_e32 v[62:63], v[2:3]
	v_mov_b64_e32 v[66:67], v[2:3]
	v_mov_b64_e32 v[70:71], v[2:3]
	v_mov_b64_e32 v[74:75], v[2:3]
	v_mov_b64_e32 v[86:87], v[2:3]
	v_mov_b64_e32 v[90:91], v[2:3]
	v_mov_b64_e32 v[102:103], v[2:3]
	v_mov_b64_e32 v[106:107], v[2:3]
	v_mov_b64_e32 v[118:119], v[2:3]
	v_mov_b64_e32 v[122:123], v[2:3]
	v_mov_b64_e32 v[78:79], v[2:3]
	v_mov_b64_e32 v[82:83], v[2:3]
	v_mov_b64_e32 v[94:95], v[2:3]
	v_mov_b64_e32 v[98:99], v[2:3]
	v_mov_b64_e32 v[110:111], v[2:3]
	v_mov_b64_e32 v[114:115], v[2:3]
	v_mov_b64_e32 v[126:127], v[2:3]
	v_mov_b64_e32 v[130:131], v[2:3]
	s_branch .LBB0_524

.LBB0_604:
	s_add_i32 s11, s59, 0x100
	s_lshl_b32 s9, s78, 20
	s_and_b64 s[80:81], s[4:5], exec
	s_cselect_b32 s79, s9, s64
	s_lshl_b32 s10, s77, 20
	s_and_b64 s[80:81], s[4:5], exec
	s_cselect_b32 s80, s10, s59
	s_cselect_b32 s98, 0, 0xf00
	s_add_i32 s79, s79, s98
	s_add_i32 s80, s80, s98
	s_mov_b32 s81, -2
	s_mov_b32 s82, 0

.LBB0_821:
	s_lshl_b32 s88, s87, 20
	s_and_b64 s[10:11], s[8:9], exec
	s_cselect_b32 s10, s88, s68
	s_lshl_b32 s89, s86, 19
	s_and_b64 s[92:93], s[8:9], exec
	v_mov_b32_e32 v2, 0
	s_cselect_b32 s11, s89, s67
	s_cselect_b32 s98, 0, 0xf00
	s_add_i32 s10, s10, s98
	s_add_i32 s11, s11, s98
	s_addk_i32 s67, 0x100
	s_add_i32 s68, s68, 0x80080
	s_mov_b32 s69, -2
	v_mov_b32_e32 v3, v2
	v_mov_b32_e32 v4, v2
	v_mov_b32_e32 v5, v2
	v_mov_b32_e32 v6, v2
	v_mov_b32_e32 v7, v2
	v_mov_b32_e32 v8, v2
	s_waitcnt vmcnt(38)
	v_mov_b32_e32 v9, v2
	v_mov_b32_e32 v10, v2
	s_waitcnt vmcnt(36)
	v_mov_b32_e32 v11, v2
	v_mov_b32_e32 v12, v2
	s_waitcnt vmcnt(34)
	v_mov_b32_e32 v13, v2
	s_waitcnt vmcnt(31)
	v_mov_b32_e32 v18, v2
	s_waitcnt vmcnt(28)
	v_mov_b32_e32 v19, v2
	v_mov_b32_e32 v20, v2
	s_waitcnt vmcnt(26)
	v_mov_b32_e32 v21, v2
	v_mov_b32_e32 v14, v2
	v_mov_b32_e32 v15, v2
	v_mov_b32_e32 v16, v2
	v_mov_b32_e32 v17, v2
	v_mov_b32_e32 v22, v2
	s_waitcnt vmcnt(24)
	v_mov_b32_e32 v23, v2
	v_mov_b32_e32 v24, v2
	s_waitcnt vmcnt(22)
	v_mov_b32_e32 v25, v2
	v_mov_b32_e32 v50, v2
	v_mov_b32_e32 v51, v2
	v_mov_b32_e32 v52, v2
	v_mov_b32_e32 v53, v2
	v_mov_b32_e32 v54, v2
	v_mov_b32_e32 v55, v2
	v_mov_b32_e32 v56, v2
	v_mov_b32_e32 v57, v2
	v_mov_b32_e32 v26, v2
	s_waitcnt vmcnt(20)
	v_mov_b32_e32 v27, v2
	v_mov_b32_e32 v28, v2
	s_waitcnt vmcnt(18)
	v_mov_b32_e32 v29, v2
	v_mov_b32_e32 v30, v2
	s_waitcnt vmcnt(16)
	v_mov_b32_e32 v31, v2
	v_mov_b32_e32 v32, v2
	v_mov_b32_e32 v33, v2
	v_mov_b32_e32 v34, v2
	v_mov_b32_e32 v35, v2
	v_mov_b32_e32 v36, v2
	v_mov_b32_e32 v37, v2
	v_mov_b32_e32 v42, v2
	v_mov_b32_e32 v43, v2
	v_mov_b32_e32 v44, v2
	v_mov_b32_e32 v45, v2
	v_mov_b32_e32 v38, v2
	v_mov_b32_e32 v39, v2
	v_mov_b32_e32 v40, v2
	v_mov_b32_e32 v41, v2
	v_mov_b32_e32 v46, v2
	v_mov_b32_e32 v47, v2
	v_mov_b32_e32 v48, v2
	v_mov_b32_e32 v49, v2
	v_mov_b32_e32 v58, v2
	v_mov_b32_e32 v59, v2
	v_mov_b32_e32 v60, v2
	v_mov_b32_e32 v61, v2
	v_mov_b32_e32 v62, v2
	v_mov_b32_e32 v63, v2
	v_mov_b32_e32 v64, v2
	v_mov_b32_e32 v65, v2
	v_mov_b32_e32 v130, v2
	v_mov_b32_e32 v131, v2
	v_mov_b32_e32 v132, v2
	v_mov_b32_e32 v133, v2
	v_mov_b32_e32 v134, v2
	v_mov_b32_e32 v135, v2
	v_mov_b32_e32 v136, v2
	v_mov_b32_e32 v137, v2
	v_mov_b32_e32 v138, v2
	v_mov_b32_e32 v139, v2
	v_mov_b32_e32 v140, v2
	v_mov_b32_e32 v141, v2
	v_mov_b32_e32 v146, v2
	v_mov_b32_e32 v147, v2
	v_mov_b32_e32 v148, v2
	v_mov_b32_e32 v149, v2
	v_mov_b32_e32 v142, v2
	v_mov_b32_e32 v143, v2
	v_mov_b32_e32 v144, v2
	v_mov_b32_e32 v145, v2
	v_mov_b32_e32 v150, v2
	v_mov_b32_e32 v151, v2
	v_mov_b32_e32 v152, v2
	v_mov_b32_e32 v153, v2
	v_mov_b32_e32 v178, v2
	v_mov_b32_e32 v179, v2
	v_mov_b32_e32 v180, v2
	v_mov_b32_e32 v181, v2
	v_mov_b32_e32 v182, v2
	v_mov_b32_e32 v183, v2
	v_mov_b32_e32 v184, v2
	v_mov_b32_e32 v185, v2
	v_mov_b32_e32 v154, v2
	v_mov_b32_e32 v155, v2
	v_mov_b32_e32 v156, v2
	v_mov_b32_e32 v157, v2
	v_mov_b32_e32 v158, v2
	v_mov_b32_e32 v159, v2
	v_mov_b32_e32 v160, v2
	v_mov_b32_e32 v161, v2
	v_mov_b32_e32 v162, v2
	v_mov_b32_e32 v163, v2
	v_mov_b32_e32 v164, v2
	v_mov_b32_e32 v165, v2
	v_mov_b32_e32 v170, v2
	v_mov_b32_e32 v171, v2
	v_mov_b32_e32 v172, v2
	v_mov_b32_e32 v173, v2
	v_mov_b32_e32 v166, v2
	v_mov_b32_e32 v167, v2
	v_mov_b32_e32 v168, v2
	v_mov_b32_e32 v169, v2
	v_mov_b32_e32 v174, v2
	v_mov_b32_e32 v175, v2
	v_mov_b32_e32 v176, v2
	v_mov_b32_e32 v177, v2
	v_mov_b32_e32 v186, v2
	v_mov_b32_e32 v187, v2
	v_mov_b32_e32 v188, v2
	v_mov_b32_e32 v189, v2
	v_mov_b32_e32 v190, v2
	v_mov_b32_e32 v191, v2
	v_mov_b32_e32 v192, v2
	v_mov_b32_e32 v193, v2

.LBB0_998:
	s_mul_i32 s47, s85, 0x2c0000
	s_and_b64 s[4:5], s[6:7], exec
	s_mul_i32 s86, s84, 0x2c0000
	s_cselect_b32 s87, s47, s61
	s_cselect_b32 s88, s86, s63
	s_cselect_b32 s98, 0, 0x2b00
	s_add_i32 s87, s87, s98
	s_add_i32 s88, s88, s98
	s_cmp_gt_i32 s85, 0
	s_cselect_b64 s[4:5], -1, 0
	s_lshl_b32 s89, s85, 2
	v_cndmask_b32_e64 v140, 0, 1.0, s[4:5]
	s_mov_b32 s92, 0
	s_or_b32 s90, s89, 2
	v_mov_b32_e32 v142, v140
	v_mov_b32_e32 v143, v140
	s_lshl_b32 s91, s85, 8
